# cache copies moved from phase 0 onto the 116 workgroups idle in the in-projection's second round (1/4 per layer)
# speedup vs baseline: 1.1254x; 1.0100x over previous
; #define INP(i) ((const float*)ld_ptr(pb, (i)))
; __global__ void __launch_bounds__(512, 2) hybrid_fwd(Params P) {
;     ...
;         { const float* ckp = INP(4); const float* cvp = INP(5); const float* scp = INP(8);
; #pragma unroll 4
;         for (int i = gt; i < DEPTH * NSB * 124 * 32; i += NGT) { const int c4 = i & 31, r = (i >> 5) % 124, lb = i / (32 * 124);
;             const size_t src = ((size_t)lb * 128 + r + 4) * 128 + c4 * 4, dst = ((size_t)lb * 128 + r) * 128 + c4 * 4;
;             *(f32x4*)(out + O_KS + dst) = *(const f32x4*)(ckp + src); *(f32x4*)(out + O_VS + dst) = *(const f32x4*)(cvp + src); }
; #pragma unroll 4
;         for (int i = gt; i < DEPTH * NSB * 26 * 64; i += NGT) { const int c4 = i & 63, r = (i >> 6) % 26, lb = i / (64 * 26);
;             *(f32x4*)(out + O_CS + ((size_t)lb * 30 + r) * 256 + c4 * 4) = *(const f32x4*)(scp + ((size_t)lb * 30 + r + 4) * 256 + c4 * 4); } }
;         float* scr = (float*)(lds + wave * 16384);
;         constexpr int I_IN = 16 * 48, I_OUT = 16 * 32, I_G = 16 * 88, I_DN = 44 * 32, I_GLU = 4 * 8, I_MOD = 16 * 192;
;         constexpr int I_LAYER = I_IN + I_OUT + 2 * I_G + I_DN + I_GLU + I_MOD;
;         for (int it = gw; it < DEPTH * I_LAYER; it += NGW) {
.LBB0_56:
	s_or_b64 exec, exec, s[10:11]
	s_lshl_b32 s0, s26, 3
	s_add_i32 s10, s0, s25
	s_cmp_gt_i32 s10, 0x867f
	s_cbranch_scc1 .LBB0_116
	s_lshl_b32 s0, s25, 14
	s_lshl_b32 s11, s24, 3
	s_add_i32 s0, s0, 0
	s_add_u32 s12, s6, 0xe100000
	s_addc_u32 s13, s7, 0
	s_add_u32 s14, s6, 0x1600000
	s_addc_u32 s15, s7, 0
	s_add_u32 s16, s6, 0x6800000
	s_addc_u32 s17, s7, 0
	v_ashrrev_i32_e32 v4, 5, v24
	s_movk_i32 s2, 0x84
	s_add_u32 s18, s6, 0x3c00000
	v_mul_lo_u32 v0, v4, s2
	v_lshlrev_b32_e32 v2, 2, v8
	s_addc_u32 s19, s7, 0
	v_add3_u32 v5, s0, v0, v2
	v_lshlrev_b32_e32 v0, 3, v24
	s_add_u32 s20, s6, 0x3400000
	v_ashrrev_i32_e32 v6, 3, v24
	v_and_b32_e32 v2, 56, v0
	s_addc_u32 s21, s7, 0
	v_mul_u32_u24_e32 v0, 0x84, v2
	v_lshlrev_b32_e32 v3, 2, v6
	s_add_u32 s22, s6, 0x2800000
	s_mov_b32 s1, 0
	v_mov_b32_e32 v1, 0
	v_add3_u32 v7, s0, v0, v3
	v_add_u32_e32 v10, 8, v6
	v_add_u32_e32 v11, 16, v6
	v_add_u32_e32 v12, 24, v6
	s_addc_u32 s23, s7, 0
	s_lshl_b32 s25, s10, 1
	s_lshl_b32 s26, s24, 4
	s_lshl_b32 s27, s10, 5
	s_lshl_b32 s28, s24, 8
	s_lshl_b32 s29, s10, 3
	s_lshl_b32 s30, s24, 6
	s_movk_i32 s31, 0x6000
	s_movk_i32 s33, 0x1000
	s_movk_i32 s34, 0x2000
	s_movk_i32 s35, 0x3000
	s_movk_i32 s36, 0x4000
	s_movk_i32 s37, 0x5000
	s_movk_i32 s38, 0x7000
	s_mov_b32 s39, 0x8000
	s_mov_b32 s40, 0x9000
	s_mov_b32 s41, 0xa000
	s_mov_b32 s42, 0xb000
	s_mov_b32 s43, 0xc000
	s_mov_b32 s44, 0xd000
	s_mov_b32 s45, 0xe000
	s_mov_b32 s46, 0xf000
	s_mov_b32 s47, 0x10000
	s_mov_b32 s48, 0x12000
	s_mov_b32 s49, 0x14000
	s_mov_b32 s50, 0x16000
	s_mov_b32 s51, 0x18000
	s_mov_b32 s52, 0x1a000
	s_mov_b32 s53, 0x1c000
	s_mov_b32 s54, 0x1e000
	s_mov_b32 s55, 0x20000
	s_mov_b32 s56, 0x22000
	s_mov_b32 s57, 0x24000
	s_mov_b32 s58, 0x26000
	s_mov_b32 s59, 0x28000
	s_mov_b32 s60, 0x2a000
	s_mov_b32 s61, 0x2c000
	s_mov_b32 s62, 0x2e000
	s_mov_b32 s63, 0x30000
	s_mov_b32 s64, 0x32000
	s_mov_b32 s65, 0x34000
	s_mov_b32 s66, 0x36000
	s_mov_b32 s67, 0x38000
	s_mov_b32 s68, 0x3a000
	s_mov_b32 s69, 0x3c000
	s_mov_b32 s70, 0x3e000
	s_movk_i32 s71, 0x1600
	s_movk_i32 s72, 0x2c00
	s_movk_i32 s73, 0x1800
	v_lshlrev_b32_e32 v0, 2, v8
	v_add_u32_e32 v8, 0x400, v5
	v_add_u32_e32 v13, 0x800, v5
	v_add_u32_e32 v14, 0xc00, v5
	v_add_u32_e32 v16, 0x1000, v5
	v_add_u32_e32 v17, 0x1400, v5
	v_add_u32_e32 v18, 0x1800, v5
	v_add_u32_e32 v19, 0x1c00, v5
	v_lshlrev_b32_e32 v2, 1, v2
	s_branch .LBB0_76

; #define INP(i) ((const float*)ld_ptr(pb, (i)))
; __global__ void __launch_bounds__(512, 2) hybrid_fwd(Params P) {
;     ...
;         { const float* ckp = INP(4); const float* cvp = INP(5); const float* scp = INP(8);
; #pragma unroll 4
;         for (int i = gt; i < DEPTH * NSB * 124 * 32; i += NGT) { const int c4 = i & 31, r = (i >> 5) % 124, lb = i / (32 * 124);
;             const size_t src = ((size_t)lb * 128 + r + 4) * 128 + c4 * 4, dst = ((size_t)lb * 128 + r) * 128 + c4 * 4;
;             *(f32x4*)(out + O_KS + dst) = *(const f32x4*)(ckp + src); *(f32x4*)(out + O_VS + dst) = *(const f32x4*)(cvp + src); }
; #pragma unroll 4
;         for (int i = gt; i < DEPTH * NSB * 26 * 64; i += NGT) { const int c4 = i & 63, r = (i >> 6) % 26, lb = i / (64 * 26);
;             *(f32x4*)(out + O_CS + ((size_t)lb * 30 + r) * 256 + c4 * 4) = *(const f32x4*)(scp + ((size_t)lb * 30 + r + 4) * 256 + c4 * 4); } }
.LBB0_857:
	v_readlane_b32 s29, v253, 0
	v_readlane_b32 s30, v253, 2
	s_nop 3
	s_cmp_lt_u32 s29, 140
	s_cbranch_scc1 .Lcpx_skip
	s_sub_u32 s29, s29, 140
	s_lshl_b32 s29, s29, 3
	s_add_u32 s29, s29, s30
	v_mbcnt_lo_u32_b32 v16, -1, 0
	v_mbcnt_hi_u32_b32 v16, -1, v16
	v_lshlrev_b32_e32 v16, 4, v16
	v_mov_b32_e32 v0, 0x20420
	ds_read_b64 v[0:1], v0
	v_mov_b32_e32 v18, 0x20510
	ds_read_b64 v[18:19], v18
	s_waitcnt lgkmcnt(0)
	v_readfirstlane_b32 s10, v0
	v_readfirstlane_b32 s11, v1
	v_readfirstlane_b32 s20, v18
	v_readfirstlane_b32 s21, v19
	s_nop 0
	s_add_u32 s10, s10, 0x800
	s_addc_u32 s11, s11, 0
	s_add_u32 s20, s20, 0x4498000
	s_addc_u32 s21, s21, 0
	s_mul_i32 s1, s96, 7936
	s_add_u32 s0, s1, s29
	s_add_u32 s1, s1, 0x1eff
	s_mov_b32 s27, 0x4210843
.Lcpx_k:
	s_min_u32 s7, s0, s1
	s_mul_hi_u32 s23, s7, s27
	s_mul_i32 s18, s23, 62
	s_sub_u32 s7, s7, s18
	s_mul_i32 s23, s23, 0x10000
	s_lshl_b32 s7, s7, 10
	s_add_u32 s7, s7, s23
	v_add_u32_e32 v4, s7, v16
	global_load_dwordx4 v[88:91], v4, s[10:11]
	s_add_u32 s0, s0, 928
	s_min_u32 s7, s0, s1
	s_mul_hi_u32 s23, s7, s27
	s_mul_i32 s18, s23, 62
	s_sub_u32 s7, s7, s18
	s_mul_i32 s23, s23, 0x10000
	s_lshl_b32 s7, s7, 10
	s_add_u32 s7, s7, s23
	v_add_u32_e32 v5, s7, v16
	global_load_dwordx4 v[92:95], v5, s[10:11]
	s_add_u32 s0, s0, 928
	s_min_u32 s7, s0, s1
	s_mul_hi_u32 s23, s7, s27
	s_mul_i32 s18, s23, 62
	s_sub_u32 s7, s7, s18
	s_mul_i32 s23, s23, 0x10000
	s_lshl_b32 s7, s7, 10
	s_add_u32 s7, s7, s23
	v_add_u32_e32 v6, s7, v16
	global_load_dwordx4 v[96:99], v6, s[10:11]
	s_add_u32 s0, s0, 928
	s_min_u32 s7, s0, s1
	s_mul_hi_u32 s23, s7, s27
	s_mul_i32 s18, s23, 62
	s_sub_u32 s7, s7, s18
	s_mul_i32 s23, s23, 0x10000
	s_lshl_b32 s7, s7, 10
	s_add_u32 s7, s7, s23
	v_add_u32_e32 v7, s7, v16
	global_load_dwordx4 v[100:103], v7, s[10:11]
	s_add_u32 s0, s0, 928
	s_min_u32 s7, s0, s1
	s_mul_hi_u32 s23, s7, s27
	s_mul_i32 s18, s23, 62
	s_sub_u32 s7, s7, s18
	s_mul_i32 s23, s23, 0x10000
	s_lshl_b32 s7, s7, 10
	s_add_u32 s7, s7, s23
	v_add_u32_e32 v8, s7, v16
	global_load_dwordx4 v[104:107], v8, s[10:11]
	s_add_u32 s0, s0, 928
	s_min_u32 s7, s0, s1
	s_mul_hi_u32 s23, s7, s27
	s_mul_i32 s18, s23, 62
	s_sub_u32 s7, s7, s18
	s_mul_i32 s23, s23, 0x10000
	s_lshl_b32 s7, s7, 10
	s_add_u32 s7, s7, s23
	v_add_u32_e32 v9, s7, v16
	global_load_dwordx4 v[108:111], v9, s[10:11]
	s_add_u32 s0, s0, 928
	s_min_u32 s7, s0, s1
	s_mul_hi_u32 s23, s7, s27
	s_mul_i32 s18, s23, 62
	s_sub_u32 s7, s7, s18
	s_mul_i32 s23, s23, 0x10000
	s_lshl_b32 s7, s7, 10
	s_add_u32 s7, s7, s23
	v_add_u32_e32 v10, s7, v16
	global_load_dwordx4 v[112:115], v10, s[10:11]
	s_add_u32 s0, s0, 928
	s_min_u32 s7, s0, s1
	s_mul_hi_u32 s23, s7, s27
	s_mul_i32 s18, s23, 62
	s_sub_u32 s7, s7, s18
	s_mul_i32 s23, s23, 0x10000
	s_lshl_b32 s7, s7, 10
	s_add_u32 s7, s7, s23
	v_add_u32_e32 v11, s7, v16
	global_load_dwordx4 v[116:119], v11, s[10:11]
	s_add_u32 s0, s0, 928
	s_min_u32 s7, s0, s1
	s_mul_hi_u32 s23, s7, s27
	s_mul_i32 s18, s23, 62
	s_sub_u32 s7, s7, s18
	s_mul_i32 s23, s23, 0x10000
	s_lshl_b32 s7, s7, 10
	s_add_u32 s7, s7, s23
	v_add_u32_e32 v12, s7, v16
	global_load_dwordx4 v[120:123], v12, s[10:11]
	s_add_u32 s0, s0, 928
	s_waitcnt vmcnt(8)
	global_store_dwordx4 v4, v[88:91], s[20:21]
	s_waitcnt vmcnt(8)
	global_store_dwordx4 v5, v[92:95], s[20:21]
	s_waitcnt vmcnt(8)
	global_store_dwordx4 v6, v[96:99], s[20:21]
	s_waitcnt vmcnt(8)
	global_store_dwordx4 v7, v[100:103], s[20:21]
	s_waitcnt vmcnt(8)
	global_store_dwordx4 v8, v[104:107], s[20:21]
	s_waitcnt vmcnt(8)
	global_store_dwordx4 v9, v[108:111], s[20:21]
	s_waitcnt vmcnt(8)
	global_store_dwordx4 v10, v[112:115], s[20:21]
	s_waitcnt vmcnt(8)
	global_store_dwordx4 v11, v[116:119], s[20:21]
	s_waitcnt vmcnt(8)
	global_store_dwordx4 v12, v[120:123], s[20:21]
	s_cmp_le_u32 s0, s1
	s_cbranch_scc1 .Lcpx_k
	v_mov_b32_e32 v0, 0x20428
	ds_read_b64 v[0:1], v0
	v_mov_b32_e32 v18, 0x20510
	ds_read_b64 v[18:19], v18
	s_waitcnt lgkmcnt(0)
	v_readfirstlane_b32 s10, v0
	v_readfirstlane_b32 s11, v1
	v_readfirstlane_b32 s20, v18
	v_readfirstlane_b32 s21, v19
	s_nop 0
	s_add_u32 s10, s10, 0x800
	s_addc_u32 s11, s11, 0
	s_add_u32 s20, s20, 0x6498000
	s_addc_u32 s21, s21, 0
	s_mul_i32 s1, s96, 7936
	s_add_u32 s0, s1, s29
	s_add_u32 s1, s1, 0x1eff
	s_mov_b32 s27, 0x4210843
; #define INP(i) ((const float*)ld_ptr(pb, (i)))
; __global__ void __launch_bounds__(512, 2) hybrid_fwd(Params P) {
;     ...
;         { const float* ckp = INP(4); const float* cvp = INP(5); const float* scp = INP(8);
; #pragma unroll 4
;         for (int i = gt; i < DEPTH * NSB * 124 * 32; i += NGT) { const int c4 = i & 31, r = (i >> 5) % 124, lb = i / (32 * 124);
;             const size_t src = ((size_t)lb * 128 + r + 4) * 128 + c4 * 4, dst = ((size_t)lb * 128 + r) * 128 + c4 * 4;
;             *(f32x4*)(out + O_KS + dst) = *(const f32x4*)(ckp + src); *(f32x4*)(out + O_VS + dst) = *(const f32x4*)(cvp + src); }
; #pragma unroll 4
;         for (int i = gt; i < DEPTH * NSB * 26 * 64; i += NGT) { const int c4 = i & 63, r = (i >> 6) % 26, lb = i / (64 * 26);
;             *(f32x4*)(out + O_CS + ((size_t)lb * 30 + r) * 256 + c4 * 4) = *(const f32x4*)(scp + ((size_t)lb * 30 + r + 4) * 256 + c4 * 4); } }
.Lcpx_v:
	s_min_u32 s7, s0, s1
	s_mul_hi_u32 s23, s7, s27
	s_mul_i32 s18, s23, 62
	s_sub_u32 s7, s7, s18
	s_mul_i32 s23, s23, 0x10000
	s_lshl_b32 s7, s7, 10
	s_add_u32 s7, s7, s23
	v_add_u32_e32 v4, s7, v16
	global_load_dwordx4 v[88:91], v4, s[10:11]
	s_add_u32 s0, s0, 928
	s_min_u32 s7, s0, s1
	s_mul_hi_u32 s23, s7, s27
	s_mul_i32 s18, s23, 62
	s_sub_u32 s7, s7, s18
	s_mul_i32 s23, s23, 0x10000
	s_lshl_b32 s7, s7, 10
	s_add_u32 s7, s7, s23
	v_add_u32_e32 v5, s7, v16
	global_load_dwordx4 v[92:95], v5, s[10:11]
	s_add_u32 s0, s0, 928
	s_min_u32 s7, s0, s1
	s_mul_hi_u32 s23, s7, s27
	s_mul_i32 s18, s23, 62
	s_sub_u32 s7, s7, s18
	s_mul_i32 s23, s23, 0x10000
	s_lshl_b32 s7, s7, 10
	s_add_u32 s7, s7, s23
	v_add_u32_e32 v6, s7, v16
	global_load_dwordx4 v[96:99], v6, s[10:11]
	s_add_u32 s0, s0, 928
	s_min_u32 s7, s0, s1
	s_mul_hi_u32 s23, s7, s27
	s_mul_i32 s18, s23, 62
	s_sub_u32 s7, s7, s18
	s_mul_i32 s23, s23, 0x10000
	s_lshl_b32 s7, s7, 10
	s_add_u32 s7, s7, s23
	v_add_u32_e32 v7, s7, v16
	global_load_dwordx4 v[100:103], v7, s[10:11]
	s_add_u32 s0, s0, 928
	s_min_u32 s7, s0, s1
	s_mul_hi_u32 s23, s7, s27
	s_mul_i32 s18, s23, 62
	s_sub_u32 s7, s7, s18
	s_mul_i32 s23, s23, 0x10000
	s_lshl_b32 s7, s7, 10
	s_add_u32 s7, s7, s23
	v_add_u32_e32 v8, s7, v16
	global_load_dwordx4 v[104:107], v8, s[10:11]
	s_add_u32 s0, s0, 928
	s_min_u32 s7, s0, s1
	s_mul_hi_u32 s23, s7, s27
	s_mul_i32 s18, s23, 62
	s_sub_u32 s7, s7, s18
	s_mul_i32 s23, s23, 0x10000
	s_lshl_b32 s7, s7, 10
	s_add_u32 s7, s7, s23
	v_add_u32_e32 v9, s7, v16
	global_load_dwordx4 v[108:111], v9, s[10:11]
	s_add_u32 s0, s0, 928
	s_min_u32 s7, s0, s1
	s_mul_hi_u32 s23, s7, s27
	s_mul_i32 s18, s23, 62
	s_sub_u32 s7, s7, s18
	s_mul_i32 s23, s23, 0x10000
	s_lshl_b32 s7, s7, 10
	s_add_u32 s7, s7, s23
	v_add_u32_e32 v10, s7, v16
	global_load_dwordx4 v[112:115], v10, s[10:11]
	s_add_u32 s0, s0, 928
	s_min_u32 s7, s0, s1
	s_mul_hi_u32 s23, s7, s27
	s_mul_i32 s18, s23, 62
	s_sub_u32 s7, s7, s18
	s_mul_i32 s23, s23, 0x10000
	s_lshl_b32 s7, s7, 10
	s_add_u32 s7, s7, s23
	v_add_u32_e32 v11, s7, v16
	global_load_dwordx4 v[116:119], v11, s[10:11]
	s_add_u32 s0, s0, 928
	s_min_u32 s7, s0, s1
	s_mul_hi_u32 s23, s7, s27
	s_mul_i32 s18, s23, 62
	s_sub_u32 s7, s7, s18
	s_mul_i32 s23, s23, 0x10000
	s_lshl_b32 s7, s7, 10
	s_add_u32 s7, s7, s23
	v_add_u32_e32 v12, s7, v16
	global_load_dwordx4 v[120:123], v12, s[10:11]
	s_add_u32 s0, s0, 928
	s_waitcnt vmcnt(8)
	global_store_dwordx4 v4, v[88:91], s[20:21]
	s_waitcnt vmcnt(8)
	global_store_dwordx4 v5, v[92:95], s[20:21]
	s_waitcnt vmcnt(8)
	global_store_dwordx4 v6, v[96:99], s[20:21]
	s_waitcnt vmcnt(8)
	global_store_dwordx4 v7, v[100:103], s[20:21]
	s_waitcnt vmcnt(8)
	global_store_dwordx4 v8, v[104:107], s[20:21]
	s_waitcnt vmcnt(8)
	global_store_dwordx4 v9, v[108:111], s[20:21]
	s_waitcnt vmcnt(8)
	global_store_dwordx4 v10, v[112:115], s[20:21]
	s_waitcnt vmcnt(8)
	global_store_dwordx4 v11, v[116:119], s[20:21]
	s_waitcnt vmcnt(8)
	global_store_dwordx4 v12, v[120:123], s[20:21]
	s_cmp_le_u32 s0, s1
	s_cbranch_scc1 .Lcpx_v
	v_mov_b32_e32 v0, 0x20440
	ds_read_b64 v[0:1], v0
	v_mov_b32_e32 v18, 0x20510
	ds_read_b64 v[18:19], v18
	s_waitcnt lgkmcnt(0)
	v_readfirstlane_b32 s10, v0
	v_readfirstlane_b32 s11, v1
	v_readfirstlane_b32 s20, v18
	v_readfirstlane_b32 s21, v19
	s_nop 0
	s_add_u32 s10, s10, 0x1000
	s_addc_u32 s11, s11, 0
	s_add_u32 s20, s20, 0x8898000
	s_addc_u32 s21, s21, 0
	s_mul_i32 s1, s96, 3328
	s_add_u32 s0, s1, s29
	s_add_u32 s1, s1, 0xcff
	s_mov_b32 s27, 0x9d89d8a
.Lcpx_c:
	s_min_u32 s7, s0, s1
	s_mul_hi_u32 s23, s7, s27
	s_mul_i32 s18, s23, 26
	s_sub_u32 s7, s7, s18
	s_mul_i32 s23, s23, 0x7800
	s_lshl_b32 s7, s7, 10
	s_add_u32 s7, s7, s23
	v_add_u32_e32 v4, s7, v16
	global_load_dwordx4 v[88:91], v4, s[10:11]
	s_add_u32 s0, s0, 928
	s_min_u32 s7, s0, s1
	s_mul_hi_u32 s23, s7, s27
	s_mul_i32 s18, s23, 26
	s_sub_u32 s7, s7, s18
	s_mul_i32 s23, s23, 0x7800
	s_lshl_b32 s7, s7, 10
	s_add_u32 s7, s7, s23
	v_add_u32_e32 v5, s7, v16
	global_load_dwordx4 v[92:95], v5, s[10:11]
	s_add_u32 s0, s0, 928
	s_min_u32 s7, s0, s1
	s_mul_hi_u32 s23, s7, s27
	s_mul_i32 s18, s23, 26
	s_sub_u32 s7, s7, s18
	s_mul_i32 s23, s23, 0x7800
	s_lshl_b32 s7, s7, 10
	s_add_u32 s7, s7, s23
	v_add_u32_e32 v6, s7, v16
	global_load_dwordx4 v[96:99], v6, s[10:11]
	s_add_u32 s0, s0, 928
	s_min_u32 s7, s0, s1
	s_mul_hi_u32 s23, s7, s27
	s_mul_i32 s18, s23, 26
	s_sub_u32 s7, s7, s18
	s_mul_i32 s23, s23, 0x7800
	s_lshl_b32 s7, s7, 10
	s_add_u32 s7, s7, s23
	v_add_u32_e32 v7, s7, v16
	global_load_dwordx4 v[100:103], v7, s[10:11]
	s_add_u32 s0, s0, 928
	s_waitcnt vmcnt(3)
	global_store_dwordx4 v4, v[88:91], s[20:21]
	s_waitcnt vmcnt(3)
	global_store_dwordx4 v5, v[92:95], s[20:21]
	s_waitcnt vmcnt(3)
	global_store_dwordx4 v6, v[96:99], s[20:21]
	s_waitcnt vmcnt(3)
	global_store_dwordx4 v7, v[100:103], s[20:21]
	s_cmp_le_u32 s0, s1
	s_cbranch_scc1 .Lcpx_c
